# v31 + loop-head trimming in attention tile loops (NEGM zero-init and inactive-mask computation hoisted out of the per-tile path)
# speedup vs baseline: 1.0060x; 1.0060x over previous
; template <int DQ, bool NA, int NQG>
; DI void attn_wg(const half_t* Qp, const half_t* Kp, const half_t* Vp, int q0, bool active, int seg0_start, int seg0_tiles,
;                 int seg1_start, int seg1_tiles, const float* rpb_h, int rq, char* smem, int tid, f16v (&O)[2][NQG]) {
;     ...
;     const half_t* ksm = (const half_t*)(smem + (it & 1) * ATT_STAGE) + r * KSTR + h * 8;
;     const half_t* vsm = (const half_t*)(smem + (it & 1) * ATT_STAGE + ATT_VOFF) + r * VSTR + h * 4;
;     const bool masked = NA && it < seg0_tiles;
;     const int krow = k0 >> 6;
;     const bool need = active && (!masked || (krow >= r0w && krow < r0w + 8));
;     if (need) {
; #pragma unroll 1
;       for (int st = 0; st < 2; ++st) {
;         f16v S[NQG];
; #pragma unroll
;         for (int qg = 0; qg < NQG; ++qg)
; #pragma unroll
;           for (int i = 0; i < 16; ++i) S[qg][i] = 0.f;
; #pragma unroll
;         for (int ks = 0; ks < NKS; ++ks) {
;           const h8 kf = *(const h8*)(ksm + (st * 32) * KSTR + ks * 16);
; #pragma unroll
;           for (int qg = 0; qg < NQG; ++qg) S[qg] = __builtin_amdgcn_mfma_f32_32x32x16_f16(kf, qf[qg][ks], S[qg], 0, 0, 0);
.LBB0_2039:
	s_andn2_b64 vcc, exec, s[14:15]
	s_cbranch_vccnz .LBB0_2046
	s_cmp_eq_u32 s18, 0
	s_cselect_b32 s19, 1, 0
	s_bitcmp1_b32 s18, 0
	s_cselect_b32 s18, 0x5800, 0
	ds_read_b128 v[2:5], v15 offset:0
	ds_read_b128 v[6:9], v15 offset:32
	ds_read2_b64 v[10:13], v183 offset0:0 offset1:2
	ds_read2_b64 v[136:139], v183 offset0:4 offset1:6
	ds_read2_b64 v[150:153], v187 offset0:0 offset1:2
	ds_read2_b64 v[190:193], v187 offset0:4 offset1:6
	s_waitcnt lgkmcnt(5)
	v_mfma_f32_32x32x16_f16 v[96:111], v[2:5], v[112:115], v[196:211]
	s_waitcnt lgkmcnt(4)
	v_mfma_f32_32x32x16_f16 v[96:111], v[6:9], v[116:119], v[96:111]
	s_cmp_lg_u32 s19, 0
	s_cbranch_scc1 .Lfirst_diff1c_0
